# S5 pass 1 rewritten by hand: per-half Horner with packed f32 FMAs, one carry per lane half, halves merged once per chunk (same f32 math on the same bf16 MFMA products)
# speedup vs baseline: 1.0182x; 1.0013x over previous
.LBB0_747:
	s_and_b32 s10, s16, 31
	v_mov_b32_e32 v122, v228
	s_lshl_b32 s60, s10, 8
	v_ashrrev_i32_e32 v123, 31, v122
	s_waitcnt lgkmcnt(14)
	v_lshl_add_u64 v[2:3], v[122:123], 0, s[60:61]
	v_lshl_add_u64 v[2:3], v[2:3], 4, s[6:7]
	s_or_b32 s18, s60, 64
	s_mov_b32 s19, s61
	global_load_dwordx4 v[90:93], v[2:3], off
	v_lshl_add_u64 v[2:3], v[122:123], 0, s[18:19]
	v_lshl_add_u64 v[2:3], v[2:3], 4, s[6:7]
	s_or_b32 s18, s60, 0x80
	global_load_dwordx4 v[86:89], v[2:3], off
	v_lshl_add_u64 v[2:3], v[122:123], 0, s[18:19]
	v_lshl_add_u64 v[2:3], v[2:3], 4, s[6:7]
	s_or_b32 s60, s60, 0xc0
	s_ashr_i32 s4, s16, 10
	s_waitcnt lgkmcnt(4)
	global_load_dwordx4 v[78:81], v[2:3], off
	v_lshl_add_u64 v[2:3], v[122:123], 0, s[60:61]
	s_bfe_u32 s11, s16, 0x50005
	v_lshl_add_u64 v[2:3], v[2:3], 4, s[6:7]
	v_and_b32_e32 v123, 31, v122
	s_lshl_b32 s2, s10, 11
	s_ashr_i32 s5, s4, 31
	s_waitcnt lgkmcnt(0)
	global_load_dwordx4 v[82:85], v[2:3], off
	v_lshl_or_b32 v2, v123, 5, s2
	s_lshl_b64 s[4:5], s[4:5], 13
	s_lshl_b32 s2, s11, 8
	global_load_dwordx4 v[70:73], v2, s[8:9] offset:16
	global_load_dwordx4 v[74:77], v2, s[8:9]
	global_load_dwordx4 v[132:135], v2, s[8:9] offset:1040
	s_or_b32 s2, s4, s2
	global_load_dwordx4 v[128:131], v2, s[8:9] offset:1024
	v_or_b32_e32 v2, s2, v123
	s_lshl_b32 s2, s10, 5
	v_ashrrev_i32_e32 v4, 2, v122
	s_add_u32 s4, s12, s2
	v_and_b32_e32 v4, -8, v4
	v_mov_b32_e32 v3, s5
	s_addc_u32 s5, s13, 0
	v_ashrrev_i32_e32 v5, 31, v4
	v_lshl_add_u64 v[4:5], v[4:5], 1, s[4:5]
	v_lshlrev_b64 v[2:3], 10, v[2:3]
	v_lshl_add_u64 v[6:7], v[4:5], 0, v[2:3]
	global_load_dwordx4 v[156:159], v[6:7], off
	s_mov_b32 s2, 0x8000
	v_add_co_u32_e32 v8, vcc, s2, v6
	s_nop 1
	v_addc_co_u32_e32 v9, vcc, 0, v7, vcc
	global_load_dwordx4 v[118:121], v[8:9], off
	s_mov_b32 s2, 0x10000
	v_add_co_u32_e32 v8, vcc, s2, v6
	s_nop 1
	v_addc_co_u32_e32 v9, vcc, 0, v7, vcc
	global_load_dwordx4 v[114:117], v[8:9], off
	s_mov_b32 s2, 0x18000
	v_add_co_u32_e32 v8, vcc, s2, v6
	s_nop 1
	v_addc_co_u32_e32 v9, vcc, 0, v7, vcc
	global_load_dwordx4 v[110:113], v[8:9], off
	s_mov_b32 s2, 0x20000
	v_add_co_u32_e32 v8, vcc, s2, v6
	s_nop 1
	v_addc_co_u32_e32 v9, vcc, 0, v7, vcc
	global_load_dwordx4 v[106:109], v[8:9], off
	s_mov_b32 s2, 0x28000
	v_add_co_u32_e32 v8, vcc, s2, v6
	s_nop 1
	v_addc_co_u32_e32 v9, vcc, 0, v7, vcc
	global_load_dwordx4 v[102:105], v[8:9], off
	s_mov_b32 s2, 0x30000
	v_add_co_u32_e32 v8, vcc, s2, v6
	s_nop 1
	v_addc_co_u32_e32 v9, vcc, 0, v7, vcc
	global_load_dwordx4 v[98:101], v[8:9], off
	s_mov_b32 s2, 0x38000
	v_add_co_u32_e32 v6, vcc, s2, v6
	s_nop 1
	v_addc_co_u32_e32 v7, vcc, 0, v7, vcc
	global_load_dwordx4 v[94:97], v[6:7], off
	v_cmp_gt_u32_e32 vcc, 32, v122
	s_waitcnt vmcnt(7)
	v_mfma_f32_32x32x16_bf16 v[50:65], v[156:159], v[90:93], 0
	v_mfma_f32_32x32x16_bf16 v[18:33], v[156:159], v[86:89], 0
	v_mfma_f32_32x32x16_bf16 v[34:49], v[156:159], v[78:81], 0
	v_mfma_f32_32x32x16_bf16 v[2:17], v[156:159], v[82:85], 0
	v_mul_f32_e32 v136, v76, v72
	v_mul_f32_e32 v137, v76, v73
	v_mul_f32_e32 v150, v72, v72
	v_mul_f32_e32 v151, v72, v73
	v_fma_f32 v136, -v77, v73, v136
	v_fmac_f32_e32 v137, v77, v72
	v_fma_f32 v150, -v73, v73, v150
	v_add_f32_e32 v151, v151, v151
	v_mul_f32_e32 v138, v150, v150
	v_mul_f32_e32 v139, v150, v151
	v_fma_f32 v138, -v151, v151, v138
	v_add_f32_e32 v139, v139, v139
	v_mul_f32_e32 v150, v138, v138
	v_mul_f32_e32 v151, v138, v139
	v_fma_f32 v150, -v139, v139, v150
	v_add_f32_e32 v151, v151, v151
	v_mov_b32_e32 v138, v150
	v_mov_b32_e32 v139, v151
	v_mov_b32_e32 v144, 0
	v_mov_b32_e32 v145, 0
	v_mul_f32_e32 v140, v130, v134
	v_mul_f32_e32 v141, v130, v135
	v_mul_f32_e32 v152, v134, v134
	v_mul_f32_e32 v153, v134, v135
	v_fma_f32 v140, -v131, v135, v140
	v_fmac_f32_e32 v141, v131, v134
	v_fma_f32 v152, -v135, v135, v152
	v_add_f32_e32 v153, v153, v153
	v_mul_f32_e32 v142, v152, v152
	v_mul_f32_e32 v143, v152, v153
	v_fma_f32 v142, -v153, v153, v142
	v_add_f32_e32 v143, v143, v143
	v_mul_f32_e32 v152, v142, v142
	v_mul_f32_e32 v153, v142, v143
	v_fma_f32 v152, -v143, v143, v152
	v_add_f32_e32 v153, v153, v153
	v_mov_b32_e32 v142, v152
	v_mov_b32_e32 v143, v153
	v_mov_b32_e32 v146, 0
	v_mov_b32_e32 v147, 0
	v_pk_fma_f32 v[52:53], v[50:51], v[76:77], v[52:53] op_sel_hi:[1,0,1]
	v_pk_fma_f32 v[20:21], v[18:19], v[130:131], v[20:21] op_sel_hi:[1,0,1]
	v_pk_fma_f32 v[36:37], v[50:51], v[76:77], v[36:37] op_sel:[0,1,0] op_sel_hi:[1,1,1]
	v_pk_fma_f32 v[4:5], v[18:19], v[130:131], v[4:5] op_sel:[0,1,0] op_sel_hi:[1,1,1]
	v_pk_fma_f32 v[52:53], v[34:35], v[76:77], v[52:53] op_sel:[0,1,0] op_sel_hi:[1,1,1] neg_lo:[0,1,0] neg_hi:[0,1,0]
	v_pk_fma_f32 v[20:21], v[2:3], v[130:131], v[20:21] op_sel:[0,1,0] op_sel_hi:[1,1,1] neg_lo:[0,1,0] neg_hi:[0,1,0]
	v_pk_fma_f32 v[36:37], v[34:35], v[76:77], v[36:37] op_sel_hi:[1,0,1]
	v_pk_fma_f32 v[4:5], v[2:3], v[130:131], v[4:5] op_sel_hi:[1,0,1]
	v_pk_fma_f32 v[54:55], v[52:53], v[136:137], v[54:55] op_sel_hi:[1,0,1]
	v_pk_fma_f32 v[22:23], v[20:21], v[140:141], v[22:23] op_sel_hi:[1,0,1]
	v_pk_fma_f32 v[38:39], v[52:53], v[136:137], v[38:39] op_sel:[0,1,0] op_sel_hi:[1,1,1]
	v_pk_fma_f32 v[6:7], v[20:21], v[140:141], v[6:7] op_sel:[0,1,0] op_sel_hi:[1,1,1]
	v_pk_fma_f32 v[54:55], v[36:37], v[136:137], v[54:55] op_sel:[0,1,0] op_sel_hi:[1,1,1] neg_lo:[0,1,0] neg_hi:[0,1,0]
	v_pk_fma_f32 v[22:23], v[4:5], v[140:141], v[22:23] op_sel:[0,1,0] op_sel_hi:[1,1,1] neg_lo:[0,1,0] neg_hi:[0,1,0]
	v_pk_fma_f32 v[38:39], v[36:37], v[136:137], v[38:39] op_sel_hi:[1,0,1]
	v_pk_fma_f32 v[6:7], v[4:5], v[140:141], v[6:7] op_sel_hi:[1,0,1]
	v_pk_fma_f32 v[56:57], v[54:55], v[76:77], v[56:57] op_sel_hi:[1,0,1]
	v_pk_fma_f32 v[24:25], v[22:23], v[130:131], v[24:25] op_sel_hi:[1,0,1]
	v_pk_fma_f32 v[40:41], v[54:55], v[76:77], v[40:41] op_sel:[0,1,0] op_sel_hi:[1,1,1]
	v_pk_fma_f32 v[8:9], v[22:23], v[130:131], v[8:9] op_sel:[0,1,0] op_sel_hi:[1,1,1]
	v_pk_fma_f32 v[56:57], v[38:39], v[76:77], v[56:57] op_sel:[0,1,0] op_sel_hi:[1,1,1] neg_lo:[0,1,0] neg_hi:[0,1,0]
	v_pk_fma_f32 v[24:25], v[6:7], v[130:131], v[24:25] op_sel:[0,1,0] op_sel_hi:[1,1,1] neg_lo:[0,1,0] neg_hi:[0,1,0]
	v_pk_fma_f32 v[40:41], v[38:39], v[76:77], v[40:41] op_sel_hi:[1,0,1]
	v_pk_fma_f32 v[8:9], v[6:7], v[130:131], v[8:9] op_sel_hi:[1,0,1]
	v_pk_fma_f32 v[58:59], v[56:57], v[136:137], v[58:59] op_sel_hi:[1,0,1]
	v_pk_fma_f32 v[26:27], v[24:25], v[140:141], v[26:27] op_sel_hi:[1,0,1]
	v_pk_fma_f32 v[42:43], v[56:57], v[136:137], v[42:43] op_sel:[0,1,0] op_sel_hi:[1,1,1]
	v_pk_fma_f32 v[10:11], v[24:25], v[140:141], v[10:11] op_sel:[0,1,0] op_sel_hi:[1,1,1]
	v_pk_fma_f32 v[58:59], v[40:41], v[136:137], v[58:59] op_sel:[0,1,0] op_sel_hi:[1,1,1] neg_lo:[0,1,0] neg_hi:[0,1,0]
	v_pk_fma_f32 v[26:27], v[8:9], v[140:141], v[26:27] op_sel:[0,1,0] op_sel_hi:[1,1,1] neg_lo:[0,1,0] neg_hi:[0,1,0]
	v_pk_fma_f32 v[42:43], v[40:41], v[136:137], v[42:43] op_sel_hi:[1,0,1]
	v_pk_fma_f32 v[10:11], v[8:9], v[140:141], v[10:11] op_sel_hi:[1,0,1]
	v_pk_fma_f32 v[60:61], v[58:59], v[76:77], v[60:61] op_sel_hi:[1,0,1]
	v_pk_fma_f32 v[28:29], v[26:27], v[130:131], v[28:29] op_sel_hi:[1,0,1]
	v_pk_fma_f32 v[44:45], v[58:59], v[76:77], v[44:45] op_sel:[0,1,0] op_sel_hi:[1,1,1]
	v_pk_fma_f32 v[12:13], v[26:27], v[130:131], v[12:13] op_sel:[0,1,0] op_sel_hi:[1,1,1]
	v_pk_fma_f32 v[60:61], v[42:43], v[76:77], v[60:61] op_sel:[0,1,0] op_sel_hi:[1,1,1] neg_lo:[0,1,0] neg_hi:[0,1,0]
	v_pk_fma_f32 v[28:29], v[10:11], v[130:131], v[28:29] op_sel:[0,1,0] op_sel_hi:[1,1,1] neg_lo:[0,1,0] neg_hi:[0,1,0]
	v_pk_fma_f32 v[44:45], v[42:43], v[76:77], v[44:45] op_sel_hi:[1,0,1]
	v_pk_fma_f32 v[12:13], v[10:11], v[130:131], v[12:13] op_sel_hi:[1,0,1]
	v_pk_fma_f32 v[62:63], v[60:61], v[136:137], v[62:63] op_sel_hi:[1,0,1]
	v_pk_fma_f32 v[30:31], v[28:29], v[140:141], v[30:31] op_sel_hi:[1,0,1]
	v_pk_fma_f32 v[46:47], v[60:61], v[136:137], v[46:47] op_sel:[0,1,0] op_sel_hi:[1,1,1]
	v_pk_fma_f32 v[14:15], v[28:29], v[140:141], v[14:15] op_sel:[0,1,0] op_sel_hi:[1,1,1]
	v_pk_fma_f32 v[62:63], v[44:45], v[136:137], v[62:63] op_sel:[0,1,0] op_sel_hi:[1,1,1] neg_lo:[0,1,0] neg_hi:[0,1,0]
	v_pk_fma_f32 v[30:31], v[12:13], v[140:141], v[30:31] op_sel:[0,1,0] op_sel_hi:[1,1,1] neg_lo:[0,1,0] neg_hi:[0,1,0]
	v_pk_fma_f32 v[46:47], v[44:45], v[136:137], v[46:47] op_sel_hi:[1,0,1]
	v_pk_fma_f32 v[14:15], v[12:13], v[140:141], v[14:15] op_sel_hi:[1,0,1]
	v_pk_fma_f32 v[64:65], v[62:63], v[76:77], v[64:65] op_sel_hi:[1,0,1]
	v_pk_fma_f32 v[32:33], v[30:31], v[130:131], v[32:33] op_sel_hi:[1,0,1]
	v_pk_fma_f32 v[48:49], v[62:63], v[76:77], v[48:49] op_sel:[0,1,0] op_sel_hi:[1,1,1]
	v_pk_fma_f32 v[16:17], v[30:31], v[130:131], v[16:17] op_sel:[0,1,0] op_sel_hi:[1,1,1]
	v_pk_fma_f32 v[64:65], v[46:47], v[76:77], v[64:65] op_sel:[0,1,0] op_sel_hi:[1,1,1] neg_lo:[0,1,0] neg_hi:[0,1,0]
	v_pk_fma_f32 v[32:33], v[14:15], v[130:131], v[32:33] op_sel:[0,1,0] op_sel_hi:[1,1,1] neg_lo:[0,1,0] neg_hi:[0,1,0]
	v_pk_fma_f32 v[48:49], v[46:47], v[76:77], v[48:49] op_sel_hi:[1,0,1]
	v_pk_fma_f32 v[16:17], v[14:15], v[130:131], v[16:17] op_sel_hi:[1,0,1]
	v_fmac_f32_e32 v65, v74, v64
	v_fmac_f32_e32 v33, v128, v32
	v_fmac_f32_e32 v49, v75, v64
	v_fmac_f32_e32 v17, v129, v32
	v_fma_f32 v65, -v75, v48, v65
	v_fma_f32 v33, -v129, v16, v33
	v_fmac_f32_e32 v49, v74, v48
	v_fmac_f32_e32 v17, v128, v16
	v_mov_b32_e32 v148, v144
	v_mov_b32_e32 v149, v146
	v_fma_f32 v144, v138, v144, v65
	v_fma_f32 v146, v142, v146, v33
	v_fma_f32 v144, -v139, v145, v144
	v_fma_f32 v146, -v143, v147, v146
	v_fma_f32 v145, v138, v145, v49
	v_fma_f32 v147, v142, v147, v17
	v_fmac_f32_e32 v145, v139, v148
	v_fmac_f32_e32 v147, v143, v149
	s_waitcnt vmcnt(6)
	v_mfma_f32_32x32x16_bf16 v[50:65], v[118:121], v[90:93], 0
	v_mfma_f32_32x32x16_bf16 v[18:33], v[118:121], v[86:89], 0
	v_mfma_f32_32x32x16_bf16 v[34:49], v[118:121], v[78:81], 0
	v_mfma_f32_32x32x16_bf16 v[2:17], v[118:121], v[82:85], 0
	s_nop 11
	v_pk_fma_f32 v[52:53], v[50:51], v[76:77], v[52:53] op_sel_hi:[1,0,1]
	v_pk_fma_f32 v[20:21], v[18:19], v[130:131], v[20:21] op_sel_hi:[1,0,1]
	v_pk_fma_f32 v[36:37], v[50:51], v[76:77], v[36:37] op_sel:[0,1,0] op_sel_hi:[1,1,1]
	v_pk_fma_f32 v[4:5], v[18:19], v[130:131], v[4:5] op_sel:[0,1,0] op_sel_hi:[1,1,1]
	v_pk_fma_f32 v[52:53], v[34:35], v[76:77], v[52:53] op_sel:[0,1,0] op_sel_hi:[1,1,1] neg_lo:[0,1,0] neg_hi:[0,1,0]
	v_pk_fma_f32 v[20:21], v[2:3], v[130:131], v[20:21] op_sel:[0,1,0] op_sel_hi:[1,1,1] neg_lo:[0,1,0] neg_hi:[0,1,0]
	v_pk_fma_f32 v[36:37], v[34:35], v[76:77], v[36:37] op_sel_hi:[1,0,1]
	v_pk_fma_f32 v[4:5], v[2:3], v[130:131], v[4:5] op_sel_hi:[1,0,1]
	v_pk_fma_f32 v[54:55], v[52:53], v[136:137], v[54:55] op_sel_hi:[1,0,1]
	v_pk_fma_f32 v[22:23], v[20:21], v[140:141], v[22:23] op_sel_hi:[1,0,1]
	v_pk_fma_f32 v[38:39], v[52:53], v[136:137], v[38:39] op_sel:[0,1,0] op_sel_hi:[1,1,1]
	v_pk_fma_f32 v[6:7], v[20:21], v[140:141], v[6:7] op_sel:[0,1,0] op_sel_hi:[1,1,1]
	v_pk_fma_f32 v[54:55], v[36:37], v[136:137], v[54:55] op_sel:[0,1,0] op_sel_hi:[1,1,1] neg_lo:[0,1,0] neg_hi:[0,1,0]
	v_pk_fma_f32 v[22:23], v[4:5], v[140:141], v[22:23] op_sel:[0,1,0] op_sel_hi:[1,1,1] neg_lo:[0,1,0] neg_hi:[0,1,0]
	v_pk_fma_f32 v[38:39], v[36:37], v[136:137], v[38:39] op_sel_hi:[1,0,1]
	v_pk_fma_f32 v[6:7], v[4:5], v[140:141], v[6:7] op_sel_hi:[1,0,1]
	v_pk_fma_f32 v[56:57], v[54:55], v[76:77], v[56:57] op_sel_hi:[1,0,1]
	v_pk_fma_f32 v[24:25], v[22:23], v[130:131], v[24:25] op_sel_hi:[1,0,1]
	v_pk_fma_f32 v[40:41], v[54:55], v[76:77], v[40:41] op_sel:[0,1,0] op_sel_hi:[1,1,1]
	v_pk_fma_f32 v[8:9], v[22:23], v[130:131], v[8:9] op_sel:[0,1,0] op_sel_hi:[1,1,1]
	v_pk_fma_f32 v[56:57], v[38:39], v[76:77], v[56:57] op_sel:[0,1,0] op_sel_hi:[1,1,1] neg_lo:[0,1,0] neg_hi:[0,1,0]
	v_pk_fma_f32 v[24:25], v[6:7], v[130:131], v[24:25] op_sel:[0,1,0] op_sel_hi:[1,1,1] neg_lo:[0,1,0] neg_hi:[0,1,0]
	v_pk_fma_f32 v[40:41], v[38:39], v[76:77], v[40:41] op_sel_hi:[1,0,1]
	v_pk_fma_f32 v[8:9], v[6:7], v[130:131], v[8:9] op_sel_hi:[1,0,1]
	v_pk_fma_f32 v[58:59], v[56:57], v[136:137], v[58:59] op_sel_hi:[1,0,1]
	v_pk_fma_f32 v[26:27], v[24:25], v[140:141], v[26:27] op_sel_hi:[1,0,1]
	v_pk_fma_f32 v[42:43], v[56:57], v[136:137], v[42:43] op_sel:[0,1,0] op_sel_hi:[1,1,1]
	v_pk_fma_f32 v[10:11], v[24:25], v[140:141], v[10:11] op_sel:[0,1,0] op_sel_hi:[1,1,1]
	v_pk_fma_f32 v[58:59], v[40:41], v[136:137], v[58:59] op_sel:[0,1,0] op_sel_hi:[1,1,1] neg_lo:[0,1,0] neg_hi:[0,1,0]
	v_pk_fma_f32 v[26:27], v[8:9], v[140:141], v[26:27] op_sel:[0,1,0] op_sel_hi:[1,1,1] neg_lo:[0,1,0] neg_hi:[0,1,0]
	v_pk_fma_f32 v[42:43], v[40:41], v[136:137], v[42:43] op_sel_hi:[1,0,1]
	v_pk_fma_f32 v[10:11], v[8:9], v[140:141], v[10:11] op_sel_hi:[1,0,1]
	v_pk_fma_f32 v[60:61], v[58:59], v[76:77], v[60:61] op_sel_hi:[1,0,1]
	v_pk_fma_f32 v[28:29], v[26:27], v[130:131], v[28:29] op_sel_hi:[1,0,1]
	v_pk_fma_f32 v[44:45], v[58:59], v[76:77], v[44:45] op_sel:[0,1,0] op_sel_hi:[1,1,1]
	v_pk_fma_f32 v[12:13], v[26:27], v[130:131], v[12:13] op_sel:[0,1,0] op_sel_hi:[1,1,1]
	v_pk_fma_f32 v[60:61], v[42:43], v[76:77], v[60:61] op_sel:[0,1,0] op_sel_hi:[1,1,1] neg_lo:[0,1,0] neg_hi:[0,1,0]
	v_pk_fma_f32 v[28:29], v[10:11], v[130:131], v[28:29] op_sel:[0,1,0] op_sel_hi:[1,1,1] neg_lo:[0,1,0] neg_hi:[0,1,0]
	v_pk_fma_f32 v[44:45], v[42:43], v[76:77], v[44:45] op_sel_hi:[1,0,1]
	v_pk_fma_f32 v[12:13], v[10:11], v[130:131], v[12:13] op_sel_hi:[1,0,1]
	v_pk_fma_f32 v[62:63], v[60:61], v[136:137], v[62:63] op_sel_hi:[1,0,1]
	v_pk_fma_f32 v[30:31], v[28:29], v[140:141], v[30:31] op_sel_hi:[1,0,1]
	v_pk_fma_f32 v[46:47], v[60:61], v[136:137], v[46:47] op_sel:[0,1,0] op_sel_hi:[1,1,1]
	v_pk_fma_f32 v[14:15], v[28:29], v[140:141], v[14:15] op_sel:[0,1,0] op_sel_hi:[1,1,1]
	v_pk_fma_f32 v[62:63], v[44:45], v[136:137], v[62:63] op_sel:[0,1,0] op_sel_hi:[1,1,1] neg_lo:[0,1,0] neg_hi:[0,1,0]
	v_pk_fma_f32 v[30:31], v[12:13], v[140:141], v[30:31] op_sel:[0,1,0] op_sel_hi:[1,1,1] neg_lo:[0,1,0] neg_hi:[0,1,0]
	v_pk_fma_f32 v[46:47], v[44:45], v[136:137], v[46:47] op_sel_hi:[1,0,1]
	v_pk_fma_f32 v[14:15], v[12:13], v[140:141], v[14:15] op_sel_hi:[1,0,1]
	v_pk_fma_f32 v[64:65], v[62:63], v[76:77], v[64:65] op_sel_hi:[1,0,1]
	v_pk_fma_f32 v[32:33], v[30:31], v[130:131], v[32:33] op_sel_hi:[1,0,1]
	v_pk_fma_f32 v[48:49], v[62:63], v[76:77], v[48:49] op_sel:[0,1,0] op_sel_hi:[1,1,1]
	v_pk_fma_f32 v[16:17], v[30:31], v[130:131], v[16:17] op_sel:[0,1,0] op_sel_hi:[1,1,1]
	v_pk_fma_f32 v[64:65], v[46:47], v[76:77], v[64:65] op_sel:[0,1,0] op_sel_hi:[1,1,1] neg_lo:[0,1,0] neg_hi:[0,1,0]
	v_pk_fma_f32 v[32:33], v[14:15], v[130:131], v[32:33] op_sel:[0,1,0] op_sel_hi:[1,1,1] neg_lo:[0,1,0] neg_hi:[0,1,0]
	v_pk_fma_f32 v[48:49], v[46:47], v[76:77], v[48:49] op_sel_hi:[1,0,1]
	v_pk_fma_f32 v[16:17], v[14:15], v[130:131], v[16:17] op_sel_hi:[1,0,1]
	v_fmac_f32_e32 v65, v74, v64
	v_fmac_f32_e32 v33, v128, v32
	v_fmac_f32_e32 v49, v75, v64
	v_fmac_f32_e32 v17, v129, v32
	v_fma_f32 v65, -v75, v48, v65
	v_fma_f32 v33, -v129, v16, v33
	v_fmac_f32_e32 v49, v74, v48
	v_fmac_f32_e32 v17, v128, v16
	v_mov_b32_e32 v148, v144
	v_mov_b32_e32 v149, v146
	v_fma_f32 v144, v138, v144, v65
	v_fma_f32 v146, v142, v146, v33
	v_fma_f32 v144, -v139, v145, v144
	v_fma_f32 v146, -v143, v147, v146
	v_fma_f32 v145, v138, v145, v49
	v_fma_f32 v147, v142, v147, v17
	v_fmac_f32_e32 v145, v139, v148
	v_fmac_f32_e32 v147, v143, v149
	s_waitcnt vmcnt(5)
	v_mfma_f32_32x32x16_bf16 v[50:65], v[114:117], v[90:93], 0
	v_mfma_f32_32x32x16_bf16 v[18:33], v[114:117], v[86:89], 0
	v_mfma_f32_32x32x16_bf16 v[34:49], v[114:117], v[78:81], 0
	v_mfma_f32_32x32x16_bf16 v[2:17], v[114:117], v[82:85], 0
	s_nop 11
	v_pk_fma_f32 v[52:53], v[50:51], v[76:77], v[52:53] op_sel_hi:[1,0,1]
	v_pk_fma_f32 v[20:21], v[18:19], v[130:131], v[20:21] op_sel_hi:[1,0,1]
	v_pk_fma_f32 v[36:37], v[50:51], v[76:77], v[36:37] op_sel:[0,1,0] op_sel_hi:[1,1,1]
	v_pk_fma_f32 v[4:5], v[18:19], v[130:131], v[4:5] op_sel:[0,1,0] op_sel_hi:[1,1,1]
	v_pk_fma_f32 v[52:53], v[34:35], v[76:77], v[52:53] op_sel:[0,1,0] op_sel_hi:[1,1,1] neg_lo:[0,1,0] neg_hi:[0,1,0]
	v_pk_fma_f32 v[20:21], v[2:3], v[130:131], v[20:21] op_sel:[0,1,0] op_sel_hi:[1,1,1] neg_lo:[0,1,0] neg_hi:[0,1,0]
	v_pk_fma_f32 v[36:37], v[34:35], v[76:77], v[36:37] op_sel_hi:[1,0,1]
	v_pk_fma_f32 v[4:5], v[2:3], v[130:131], v[4:5] op_sel_hi:[1,0,1]
	v_pk_fma_f32 v[54:55], v[52:53], v[136:137], v[54:55] op_sel_hi:[1,0,1]
	v_pk_fma_f32 v[22:23], v[20:21], v[140:141], v[22:23] op_sel_hi:[1,0,1]
	v_pk_fma_f32 v[38:39], v[52:53], v[136:137], v[38:39] op_sel:[0,1,0] op_sel_hi:[1,1,1]
	v_pk_fma_f32 v[6:7], v[20:21], v[140:141], v[6:7] op_sel:[0,1,0] op_sel_hi:[1,1,1]
	v_pk_fma_f32 v[54:55], v[36:37], v[136:137], v[54:55] op_sel:[0,1,0] op_sel_hi:[1,1,1] neg_lo:[0,1,0] neg_hi:[0,1,0]
	v_pk_fma_f32 v[22:23], v[4:5], v[140:141], v[22:23] op_sel:[0,1,0] op_sel_hi:[1,1,1] neg_lo:[0,1,0] neg_hi:[0,1,0]
	v_pk_fma_f32 v[38:39], v[36:37], v[136:137], v[38:39] op_sel_hi:[1,0,1]
	v_pk_fma_f32 v[6:7], v[4:5], v[140:141], v[6:7] op_sel_hi:[1,0,1]
	v_pk_fma_f32 v[56:57], v[54:55], v[76:77], v[56:57] op_sel_hi:[1,0,1]
	v_pk_fma_f32 v[24:25], v[22:23], v[130:131], v[24:25] op_sel_hi:[1,0,1]
	v_pk_fma_f32 v[40:41], v[54:55], v[76:77], v[40:41] op_sel:[0,1,0] op_sel_hi:[1,1,1]
	v_pk_fma_f32 v[8:9], v[22:23], v[130:131], v[8:9] op_sel:[0,1,0] op_sel_hi:[1,1,1]
	v_pk_fma_f32 v[56:57], v[38:39], v[76:77], v[56:57] op_sel:[0,1,0] op_sel_hi:[1,1,1] neg_lo:[0,1,0] neg_hi:[0,1,0]
	v_pk_fma_f32 v[24:25], v[6:7], v[130:131], v[24:25] op_sel:[0,1,0] op_sel_hi:[1,1,1] neg_lo:[0,1,0] neg_hi:[0,1,0]
	v_pk_fma_f32 v[40:41], v[38:39], v[76:77], v[40:41] op_sel_hi:[1,0,1]
	v_pk_fma_f32 v[8:9], v[6:7], v[130:131], v[8:9] op_sel_hi:[1,0,1]
	v_pk_fma_f32 v[58:59], v[56:57], v[136:137], v[58:59] op_sel_hi:[1,0,1]
	v_pk_fma_f32 v[26:27], v[24:25], v[140:141], v[26:27] op_sel_hi:[1,0,1]
	v_pk_fma_f32 v[42:43], v[56:57], v[136:137], v[42:43] op_sel:[0,1,0] op_sel_hi:[1,1,1]
	v_pk_fma_f32 v[10:11], v[24:25], v[140:141], v[10:11] op_sel:[0,1,0] op_sel_hi:[1,1,1]
	v_pk_fma_f32 v[58:59], v[40:41], v[136:137], v[58:59] op_sel:[0,1,0] op_sel_hi:[1,1,1] neg_lo:[0,1,0] neg_hi:[0,1,0]
	v_pk_fma_f32 v[26:27], v[8:9], v[140:141], v[26:27] op_sel:[0,1,0] op_sel_hi:[1,1,1] neg_lo:[0,1,0] neg_hi:[0,1,0]
	v_pk_fma_f32 v[42:43], v[40:41], v[136:137], v[42:43] op_sel_hi:[1,0,1]
	v_pk_fma_f32 v[10:11], v[8:9], v[140:141], v[10:11] op_sel_hi:[1,0,1]
	v_pk_fma_f32 v[60:61], v[58:59], v[76:77], v[60:61] op_sel_hi:[1,0,1]
	v_pk_fma_f32 v[28:29], v[26:27], v[130:131], v[28:29] op_sel_hi:[1,0,1]
	v_pk_fma_f32 v[44:45], v[58:59], v[76:77], v[44:45] op_sel:[0,1,0] op_sel_hi:[1,1,1]
	v_pk_fma_f32 v[12:13], v[26:27], v[130:131], v[12:13] op_sel:[0,1,0] op_sel_hi:[1,1,1]
	v_pk_fma_f32 v[60:61], v[42:43], v[76:77], v[60:61] op_sel:[0,1,0] op_sel_hi:[1,1,1] neg_lo:[0,1,0] neg_hi:[0,1,0]
	v_pk_fma_f32 v[28:29], v[10:11], v[130:131], v[28:29] op_sel:[0,1,0] op_sel_hi:[1,1,1] neg_lo:[0,1,0] neg_hi:[0,1,0]
	v_pk_fma_f32 v[44:45], v[42:43], v[76:77], v[44:45] op_sel_hi:[1,0,1]
	v_pk_fma_f32 v[12:13], v[10:11], v[130:131], v[12:13] op_sel_hi:[1,0,1]
	v_pk_fma_f32 v[62:63], v[60:61], v[136:137], v[62:63] op_sel_hi:[1,0,1]
	v_pk_fma_f32 v[30:31], v[28:29], v[140:141], v[30:31] op_sel_hi:[1,0,1]
	v_pk_fma_f32 v[46:47], v[60:61], v[136:137], v[46:47] op_sel:[0,1,0] op_sel_hi:[1,1,1]
	v_pk_fma_f32 v[14:15], v[28:29], v[140:141], v[14:15] op_sel:[0,1,0] op_sel_hi:[1,1,1]
	v_pk_fma_f32 v[62:63], v[44:45], v[136:137], v[62:63] op_sel:[0,1,0] op_sel_hi:[1,1,1] neg_lo:[0,1,0] neg_hi:[0,1,0]
	v_pk_fma_f32 v[30:31], v[12:13], v[140:141], v[30:31] op_sel:[0,1,0] op_sel_hi:[1,1,1] neg_lo:[0,1,0] neg_hi:[0,1,0]
	v_pk_fma_f32 v[46:47], v[44:45], v[136:137], v[46:47] op_sel_hi:[1,0,1]
	v_pk_fma_f32 v[14:15], v[12:13], v[140:141], v[14:15] op_sel_hi:[1,0,1]
	v_pk_fma_f32 v[64:65], v[62:63], v[76:77], v[64:65] op_sel_hi:[1,0,1]
	v_pk_fma_f32 v[32:33], v[30:31], v[130:131], v[32:33] op_sel_hi:[1,0,1]
	v_pk_fma_f32 v[48:49], v[62:63], v[76:77], v[48:49] op_sel:[0,1,0] op_sel_hi:[1,1,1]
	v_pk_fma_f32 v[16:17], v[30:31], v[130:131], v[16:17] op_sel:[0,1,0] op_sel_hi:[1,1,1]
	v_pk_fma_f32 v[64:65], v[46:47], v[76:77], v[64:65] op_sel:[0,1,0] op_sel_hi:[1,1,1] neg_lo:[0,1,0] neg_hi:[0,1,0]
	v_pk_fma_f32 v[32:33], v[14:15], v[130:131], v[32:33] op_sel:[0,1,0] op_sel_hi:[1,1,1] neg_lo:[0,1,0] neg_hi:[0,1,0]
	v_pk_fma_f32 v[48:49], v[46:47], v[76:77], v[48:49] op_sel_hi:[1,0,1]
	v_pk_fma_f32 v[16:17], v[14:15], v[130:131], v[16:17] op_sel_hi:[1,0,1]
	v_fmac_f32_e32 v65, v74, v64
	v_fmac_f32_e32 v33, v128, v32
	v_fmac_f32_e32 v49, v75, v64
	v_fmac_f32_e32 v17, v129, v32
	v_fma_f32 v65, -v75, v48, v65
	v_fma_f32 v33, -v129, v16, v33
	v_fmac_f32_e32 v49, v74, v48
	v_fmac_f32_e32 v17, v128, v16
	v_mov_b32_e32 v148, v144
	v_mov_b32_e32 v149, v146
	v_fma_f32 v144, v138, v144, v65
	v_fma_f32 v146, v142, v146, v33
	v_fma_f32 v144, -v139, v145, v144
	v_fma_f32 v146, -v143, v147, v146
	v_fma_f32 v145, v138, v145, v49
	v_fma_f32 v147, v142, v147, v17
	v_fmac_f32_e32 v145, v139, v148
	v_fmac_f32_e32 v147, v143, v149
	s_waitcnt vmcnt(4)
	v_mfma_f32_32x32x16_bf16 v[50:65], v[110:113], v[90:93], 0
	v_mfma_f32_32x32x16_bf16 v[18:33], v[110:113], v[86:89], 0
	v_mfma_f32_32x32x16_bf16 v[34:49], v[110:113], v[78:81], 0
	v_mfma_f32_32x32x16_bf16 v[2:17], v[110:113], v[82:85], 0
	s_nop 11
	v_pk_fma_f32 v[52:53], v[50:51], v[76:77], v[52:53] op_sel_hi:[1,0,1]
	v_pk_fma_f32 v[20:21], v[18:19], v[130:131], v[20:21] op_sel_hi:[1,0,1]
	v_pk_fma_f32 v[36:37], v[50:51], v[76:77], v[36:37] op_sel:[0,1,0] op_sel_hi:[1,1,1]
	v_pk_fma_f32 v[4:5], v[18:19], v[130:131], v[4:5] op_sel:[0,1,0] op_sel_hi:[1,1,1]
	v_pk_fma_f32 v[52:53], v[34:35], v[76:77], v[52:53] op_sel:[0,1,0] op_sel_hi:[1,1,1] neg_lo:[0,1,0] neg_hi:[0,1,0]
	v_pk_fma_f32 v[20:21], v[2:3], v[130:131], v[20:21] op_sel:[0,1,0] op_sel_hi:[1,1,1] neg_lo:[0,1,0] neg_hi:[0,1,0]
	v_pk_fma_f32 v[36:37], v[34:35], v[76:77], v[36:37] op_sel_hi:[1,0,1]
	v_pk_fma_f32 v[4:5], v[2:3], v[130:131], v[4:5] op_sel_hi:[1,0,1]
	v_pk_fma_f32 v[54:55], v[52:53], v[136:137], v[54:55] op_sel_hi:[1,0,1]
	v_pk_fma_f32 v[22:23], v[20:21], v[140:141], v[22:23] op_sel_hi:[1,0,1]
	v_pk_fma_f32 v[38:39], v[52:53], v[136:137], v[38:39] op_sel:[0,1,0] op_sel_hi:[1,1,1]
	v_pk_fma_f32 v[6:7], v[20:21], v[140:141], v[6:7] op_sel:[0,1,0] op_sel_hi:[1,1,1]
	v_pk_fma_f32 v[54:55], v[36:37], v[136:137], v[54:55] op_sel:[0,1,0] op_sel_hi:[1,1,1] neg_lo:[0,1,0] neg_hi:[0,1,0]
	v_pk_fma_f32 v[22:23], v[4:5], v[140:141], v[22:23] op_sel:[0,1,0] op_sel_hi:[1,1,1] neg_lo:[0,1,0] neg_hi:[0,1,0]
	v_pk_fma_f32 v[38:39], v[36:37], v[136:137], v[38:39] op_sel_hi:[1,0,1]
	v_pk_fma_f32 v[6:7], v[4:5], v[140:141], v[6:7] op_sel_hi:[1,0,1]
	v_pk_fma_f32 v[56:57], v[54:55], v[76:77], v[56:57] op_sel_hi:[1,0,1]
	v_pk_fma_f32 v[24:25], v[22:23], v[130:131], v[24:25] op_sel_hi:[1,0,1]
	v_pk_fma_f32 v[40:41], v[54:55], v[76:77], v[40:41] op_sel:[0,1,0] op_sel_hi:[1,1,1]
	v_pk_fma_f32 v[8:9], v[22:23], v[130:131], v[8:9] op_sel:[0,1,0] op_sel_hi:[1,1,1]
	v_pk_fma_f32 v[56:57], v[38:39], v[76:77], v[56:57] op_sel:[0,1,0] op_sel_hi:[1,1,1] neg_lo:[0,1,0] neg_hi:[0,1,0]
	v_pk_fma_f32 v[24:25], v[6:7], v[130:131], v[24:25] op_sel:[0,1,0] op_sel_hi:[1,1,1] neg_lo:[0,1,0] neg_hi:[0,1,0]
	v_pk_fma_f32 v[40:41], v[38:39], v[76:77], v[40:41] op_sel_hi:[1,0,1]
	v_pk_fma_f32 v[8:9], v[6:7], v[130:131], v[8:9] op_sel_hi:[1,0,1]
	v_pk_fma_f32 v[58:59], v[56:57], v[136:137], v[58:59] op_sel_hi:[1,0,1]
	v_pk_fma_f32 v[26:27], v[24:25], v[140:141], v[26:27] op_sel_hi:[1,0,1]
	v_pk_fma_f32 v[42:43], v[56:57], v[136:137], v[42:43] op_sel:[0,1,0] op_sel_hi:[1,1,1]
	v_pk_fma_f32 v[10:11], v[24:25], v[140:141], v[10:11] op_sel:[0,1,0] op_sel_hi:[1,1,1]
	v_pk_fma_f32 v[58:59], v[40:41], v[136:137], v[58:59] op_sel:[0,1,0] op_sel_hi:[1,1,1] neg_lo:[0,1,0] neg_hi:[0,1,0]
	v_pk_fma_f32 v[26:27], v[8:9], v[140:141], v[26:27] op_sel:[0,1,0] op_sel_hi:[1,1,1] neg_lo:[0,1,0] neg_hi:[0,1,0]
	v_pk_fma_f32 v[42:43], v[40:41], v[136:137], v[42:43] op_sel_hi:[1,0,1]
	v_pk_fma_f32 v[10:11], v[8:9], v[140:141], v[10:11] op_sel_hi:[1,0,1]
	v_pk_fma_f32 v[60:61], v[58:59], v[76:77], v[60:61] op_sel_hi:[1,0,1]
	v_pk_fma_f32 v[28:29], v[26:27], v[130:131], v[28:29] op_sel_hi:[1,0,1]
	v_pk_fma_f32 v[44:45], v[58:59], v[76:77], v[44:45] op_sel:[0,1,0] op_sel_hi:[1,1,1]
	v_pk_fma_f32 v[12:13], v[26:27], v[130:131], v[12:13] op_sel:[0,1,0] op_sel_hi:[1,1,1]
	v_pk_fma_f32 v[60:61], v[42:43], v[76:77], v[60:61] op_sel:[0,1,0] op_sel_hi:[1,1,1] neg_lo:[0,1,0] neg_hi:[0,1,0]
	v_pk_fma_f32 v[28:29], v[10:11], v[130:131], v[28:29] op_sel:[0,1,0] op_sel_hi:[1,1,1] neg_lo:[0,1,0] neg_hi:[0,1,0]
	v_pk_fma_f32 v[44:45], v[42:43], v[76:77], v[44:45] op_sel_hi:[1,0,1]
	v_pk_fma_f32 v[12:13], v[10:11], v[130:131], v[12:13] op_sel_hi:[1,0,1]
	v_pk_fma_f32 v[62:63], v[60:61], v[136:137], v[62:63] op_sel_hi:[1,0,1]
	v_pk_fma_f32 v[30:31], v[28:29], v[140:141], v[30:31] op_sel_hi:[1,0,1]
	v_pk_fma_f32 v[46:47], v[60:61], v[136:137], v[46:47] op_sel:[0,1,0] op_sel_hi:[1,1,1]
	v_pk_fma_f32 v[14:15], v[28:29], v[140:141], v[14:15] op_sel:[0,1,0] op_sel_hi:[1,1,1]
	v_pk_fma_f32 v[62:63], v[44:45], v[136:137], v[62:63] op_sel:[0,1,0] op_sel_hi:[1,1,1] neg_lo:[0,1,0] neg_hi:[0,1,0]
	v_pk_fma_f32 v[30:31], v[12:13], v[140:141], v[30:31] op_sel:[0,1,0] op_sel_hi:[1,1,1] neg_lo:[0,1,0] neg_hi:[0,1,0]
	v_pk_fma_f32 v[46:47], v[44:45], v[136:137], v[46:47] op_sel_hi:[1,0,1]
	v_pk_fma_f32 v[14:15], v[12:13], v[140:141], v[14:15] op_sel_hi:[1,0,1]
	v_pk_fma_f32 v[64:65], v[62:63], v[76:77], v[64:65] op_sel_hi:[1,0,1]
	v_pk_fma_f32 v[32:33], v[30:31], v[130:131], v[32:33] op_sel_hi:[1,0,1]
	v_pk_fma_f32 v[48:49], v[62:63], v[76:77], v[48:49] op_sel:[0,1,0] op_sel_hi:[1,1,1]
	v_pk_fma_f32 v[16:17], v[30:31], v[130:131], v[16:17] op_sel:[0,1,0] op_sel_hi:[1,1,1]
	v_pk_fma_f32 v[64:65], v[46:47], v[76:77], v[64:65] op_sel:[0,1,0] op_sel_hi:[1,1,1] neg_lo:[0,1,0] neg_hi:[0,1,0]
	v_pk_fma_f32 v[32:33], v[14:15], v[130:131], v[32:33] op_sel:[0,1,0] op_sel_hi:[1,1,1] neg_lo:[0,1,0] neg_hi:[0,1,0]
	v_pk_fma_f32 v[48:49], v[46:47], v[76:77], v[48:49] op_sel_hi:[1,0,1]
	v_pk_fma_f32 v[16:17], v[14:15], v[130:131], v[16:17] op_sel_hi:[1,0,1]
	v_fmac_f32_e32 v65, v74, v64
	v_fmac_f32_e32 v33, v128, v32
	v_fmac_f32_e32 v49, v75, v64
	v_fmac_f32_e32 v17, v129, v32
	v_fma_f32 v65, -v75, v48, v65
	v_fma_f32 v33, -v129, v16, v33
	v_fmac_f32_e32 v49, v74, v48
	v_fmac_f32_e32 v17, v128, v16
	v_mov_b32_e32 v148, v144
	v_mov_b32_e32 v149, v146
	v_fma_f32 v144, v138, v144, v65
	v_fma_f32 v146, v142, v146, v33
	v_fma_f32 v144, -v139, v145, v144
	v_fma_f32 v146, -v143, v147, v146
	v_fma_f32 v145, v138, v145, v49
	v_fma_f32 v147, v142, v147, v17
	v_fmac_f32_e32 v145, v139, v148
	v_fmac_f32_e32 v147, v143, v149
	s_waitcnt vmcnt(3)
	v_mfma_f32_32x32x16_bf16 v[50:65], v[106:109], v[90:93], 0
	v_mfma_f32_32x32x16_bf16 v[18:33], v[106:109], v[86:89], 0
	v_mfma_f32_32x32x16_bf16 v[34:49], v[106:109], v[78:81], 0
	v_mfma_f32_32x32x16_bf16 v[2:17], v[106:109], v[82:85], 0
	s_nop 11
	v_pk_fma_f32 v[52:53], v[50:51], v[76:77], v[52:53] op_sel_hi:[1,0,1]
	v_pk_fma_f32 v[20:21], v[18:19], v[130:131], v[20:21] op_sel_hi:[1,0,1]
	v_pk_fma_f32 v[36:37], v[50:51], v[76:77], v[36:37] op_sel:[0,1,0] op_sel_hi:[1,1,1]
	v_pk_fma_f32 v[4:5], v[18:19], v[130:131], v[4:5] op_sel:[0,1,0] op_sel_hi:[1,1,1]
	v_pk_fma_f32 v[52:53], v[34:35], v[76:77], v[52:53] op_sel:[0,1,0] op_sel_hi:[1,1,1] neg_lo:[0,1,0] neg_hi:[0,1,0]
	v_pk_fma_f32 v[20:21], v[2:3], v[130:131], v[20:21] op_sel:[0,1,0] op_sel_hi:[1,1,1] neg_lo:[0,1,0] neg_hi:[0,1,0]
	v_pk_fma_f32 v[36:37], v[34:35], v[76:77], v[36:37] op_sel_hi:[1,0,1]
	v_pk_fma_f32 v[4:5], v[2:3], v[130:131], v[4:5] op_sel_hi:[1,0,1]
	v_pk_fma_f32 v[54:55], v[52:53], v[136:137], v[54:55] op_sel_hi:[1,0,1]
	v_pk_fma_f32 v[22:23], v[20:21], v[140:141], v[22:23] op_sel_hi:[1,0,1]
	v_pk_fma_f32 v[38:39], v[52:53], v[136:137], v[38:39] op_sel:[0,1,0] op_sel_hi:[1,1,1]
	v_pk_fma_f32 v[6:7], v[20:21], v[140:141], v[6:7] op_sel:[0,1,0] op_sel_hi:[1,1,1]
	v_pk_fma_f32 v[54:55], v[36:37], v[136:137], v[54:55] op_sel:[0,1,0] op_sel_hi:[1,1,1] neg_lo:[0,1,0] neg_hi:[0,1,0]
	v_pk_fma_f32 v[22:23], v[4:5], v[140:141], v[22:23] op_sel:[0,1,0] op_sel_hi:[1,1,1] neg_lo:[0,1,0] neg_hi:[0,1,0]
	v_pk_fma_f32 v[38:39], v[36:37], v[136:137], v[38:39] op_sel_hi:[1,0,1]
	v_pk_fma_f32 v[6:7], v[4:5], v[140:141], v[6:7] op_sel_hi:[1,0,1]
	v_pk_fma_f32 v[56:57], v[54:55], v[76:77], v[56:57] op_sel_hi:[1,0,1]
	v_pk_fma_f32 v[24:25], v[22:23], v[130:131], v[24:25] op_sel_hi:[1,0,1]
	v_pk_fma_f32 v[40:41], v[54:55], v[76:77], v[40:41] op_sel:[0,1,0] op_sel_hi:[1,1,1]
	v_pk_fma_f32 v[8:9], v[22:23], v[130:131], v[8:9] op_sel:[0,1,0] op_sel_hi:[1,1,1]
	v_pk_fma_f32 v[56:57], v[38:39], v[76:77], v[56:57] op_sel:[0,1,0] op_sel_hi:[1,1,1] neg_lo:[0,1,0] neg_hi:[0,1,0]
	v_pk_fma_f32 v[24:25], v[6:7], v[130:131], v[24:25] op_sel:[0,1,0] op_sel_hi:[1,1,1] neg_lo:[0,1,0] neg_hi:[0,1,0]
	v_pk_fma_f32 v[40:41], v[38:39], v[76:77], v[40:41] op_sel_hi:[1,0,1]
	v_pk_fma_f32 v[8:9], v[6:7], v[130:131], v[8:9] op_sel_hi:[1,0,1]
	v_pk_fma_f32 v[58:59], v[56:57], v[136:137], v[58:59] op_sel_hi:[1,0,1]
	v_pk_fma_f32 v[26:27], v[24:25], v[140:141], v[26:27] op_sel_hi:[1,0,1]
	v_pk_fma_f32 v[42:43], v[56:57], v[136:137], v[42:43] op_sel:[0,1,0] op_sel_hi:[1,1,1]
	v_pk_fma_f32 v[10:11], v[24:25], v[140:141], v[10:11] op_sel:[0,1,0] op_sel_hi:[1,1,1]
	v_pk_fma_f32 v[58:59], v[40:41], v[136:137], v[58:59] op_sel:[0,1,0] op_sel_hi:[1,1,1] neg_lo:[0,1,0] neg_hi:[0,1,0]
	v_pk_fma_f32 v[26:27], v[8:9], v[140:141], v[26:27] op_sel:[0,1,0] op_sel_hi:[1,1,1] neg_lo:[0,1,0] neg_hi:[0,1,0]
	v_pk_fma_f32 v[42:43], v[40:41], v[136:137], v[42:43] op_sel_hi:[1,0,1]
	v_pk_fma_f32 v[10:11], v[8:9], v[140:141], v[10:11] op_sel_hi:[1,0,1]
	v_pk_fma_f32 v[60:61], v[58:59], v[76:77], v[60:61] op_sel_hi:[1,0,1]
	v_pk_fma_f32 v[28:29], v[26:27], v[130:131], v[28:29] op_sel_hi:[1,0,1]
	v_pk_fma_f32 v[44:45], v[58:59], v[76:77], v[44:45] op_sel:[0,1,0] op_sel_hi:[1,1,1]
	v_pk_fma_f32 v[12:13], v[26:27], v[130:131], v[12:13] op_sel:[0,1,0] op_sel_hi:[1,1,1]
	v_pk_fma_f32 v[60:61], v[42:43], v[76:77], v[60:61] op_sel:[0,1,0] op_sel_hi:[1,1,1] neg_lo:[0,1,0] neg_hi:[0,1,0]
	v_pk_fma_f32 v[28:29], v[10:11], v[130:131], v[28:29] op_sel:[0,1,0] op_sel_hi:[1,1,1] neg_lo:[0,1,0] neg_hi:[0,1,0]
	v_pk_fma_f32 v[44:45], v[42:43], v[76:77], v[44:45] op_sel_hi:[1,0,1]
	v_pk_fma_f32 v[12:13], v[10:11], v[130:131], v[12:13] op_sel_hi:[1,0,1]
	v_pk_fma_f32 v[62:63], v[60:61], v[136:137], v[62:63] op_sel_hi:[1,0,1]
	v_pk_fma_f32 v[30:31], v[28:29], v[140:141], v[30:31] op_sel_hi:[1,0,1]
	v_pk_fma_f32 v[46:47], v[60:61], v[136:137], v[46:47] op_sel:[0,1,0] op_sel_hi:[1,1,1]
	v_pk_fma_f32 v[14:15], v[28:29], v[140:141], v[14:15] op_sel:[0,1,0] op_sel_hi:[1,1,1]
	v_pk_fma_f32 v[62:63], v[44:45], v[136:137], v[62:63] op_sel:[0,1,0] op_sel_hi:[1,1,1] neg_lo:[0,1,0] neg_hi:[0,1,0]
	v_pk_fma_f32 v[30:31], v[12:13], v[140:141], v[30:31] op_sel:[0,1,0] op_sel_hi:[1,1,1] neg_lo:[0,1,0] neg_hi:[0,1,0]
	v_pk_fma_f32 v[46:47], v[44:45], v[136:137], v[46:47] op_sel_hi:[1,0,1]
	v_pk_fma_f32 v[14:15], v[12:13], v[140:141], v[14:15] op_sel_hi:[1,0,1]
	v_pk_fma_f32 v[64:65], v[62:63], v[76:77], v[64:65] op_sel_hi:[1,0,1]
	v_pk_fma_f32 v[32:33], v[30:31], v[130:131], v[32:33] op_sel_hi:[1,0,1]
	v_pk_fma_f32 v[48:49], v[62:63], v[76:77], v[48:49] op_sel:[0,1,0] op_sel_hi:[1,1,1]
	v_pk_fma_f32 v[16:17], v[30:31], v[130:131], v[16:17] op_sel:[0,1,0] op_sel_hi:[1,1,1]
	v_pk_fma_f32 v[64:65], v[46:47], v[76:77], v[64:65] op_sel:[0,1,0] op_sel_hi:[1,1,1] neg_lo:[0,1,0] neg_hi:[0,1,0]
	v_pk_fma_f32 v[32:33], v[14:15], v[130:131], v[32:33] op_sel:[0,1,0] op_sel_hi:[1,1,1] neg_lo:[0,1,0] neg_hi:[0,1,0]
	v_pk_fma_f32 v[48:49], v[46:47], v[76:77], v[48:49] op_sel_hi:[1,0,1]
	v_pk_fma_f32 v[16:17], v[14:15], v[130:131], v[16:17] op_sel_hi:[1,0,1]
	v_fmac_f32_e32 v65, v74, v64
	v_fmac_f32_e32 v33, v128, v32
	v_fmac_f32_e32 v49, v75, v64
	v_fmac_f32_e32 v17, v129, v32
	v_fma_f32 v65, -v75, v48, v65
	v_fma_f32 v33, -v129, v16, v33
	v_fmac_f32_e32 v49, v74, v48
	v_fmac_f32_e32 v17, v128, v16
	v_mov_b32_e32 v148, v144
	v_mov_b32_e32 v149, v146
	v_fma_f32 v144, v138, v144, v65
	v_fma_f32 v146, v142, v146, v33
	v_fma_f32 v144, -v139, v145, v144
	v_fma_f32 v146, -v143, v147, v146
	v_fma_f32 v145, v138, v145, v49
	v_fma_f32 v147, v142, v147, v17
	v_fmac_f32_e32 v145, v139, v148
	v_fmac_f32_e32 v147, v143, v149
	s_waitcnt vmcnt(2)
	v_mfma_f32_32x32x16_bf16 v[50:65], v[102:105], v[90:93], 0
	v_mfma_f32_32x32x16_bf16 v[18:33], v[102:105], v[86:89], 0
	v_mfma_f32_32x32x16_bf16 v[34:49], v[102:105], v[78:81], 0
	v_mfma_f32_32x32x16_bf16 v[2:17], v[102:105], v[82:85], 0
	s_nop 11
	v_pk_fma_f32 v[52:53], v[50:51], v[76:77], v[52:53] op_sel_hi:[1,0,1]
	v_pk_fma_f32 v[20:21], v[18:19], v[130:131], v[20:21] op_sel_hi:[1,0,1]
	v_pk_fma_f32 v[36:37], v[50:51], v[76:77], v[36:37] op_sel:[0,1,0] op_sel_hi:[1,1,1]
	v_pk_fma_f32 v[4:5], v[18:19], v[130:131], v[4:5] op_sel:[0,1,0] op_sel_hi:[1,1,1]
	v_pk_fma_f32 v[52:53], v[34:35], v[76:77], v[52:53] op_sel:[0,1,0] op_sel_hi:[1,1,1] neg_lo:[0,1,0] neg_hi:[0,1,0]
	v_pk_fma_f32 v[20:21], v[2:3], v[130:131], v[20:21] op_sel:[0,1,0] op_sel_hi:[1,1,1] neg_lo:[0,1,0] neg_hi:[0,1,0]
	v_pk_fma_f32 v[36:37], v[34:35], v[76:77], v[36:37] op_sel_hi:[1,0,1]
	v_pk_fma_f32 v[4:5], v[2:3], v[130:131], v[4:5] op_sel_hi:[1,0,1]
	v_pk_fma_f32 v[54:55], v[52:53], v[136:137], v[54:55] op_sel_hi:[1,0,1]
	v_pk_fma_f32 v[22:23], v[20:21], v[140:141], v[22:23] op_sel_hi:[1,0,1]
	v_pk_fma_f32 v[38:39], v[52:53], v[136:137], v[38:39] op_sel:[0,1,0] op_sel_hi:[1,1,1]
	v_pk_fma_f32 v[6:7], v[20:21], v[140:141], v[6:7] op_sel:[0,1,0] op_sel_hi:[1,1,1]
	v_pk_fma_f32 v[54:55], v[36:37], v[136:137], v[54:55] op_sel:[0,1,0] op_sel_hi:[1,1,1] neg_lo:[0,1,0] neg_hi:[0,1,0]
	v_pk_fma_f32 v[22:23], v[4:5], v[140:141], v[22:23] op_sel:[0,1,0] op_sel_hi:[1,1,1] neg_lo:[0,1,0] neg_hi:[0,1,0]
	v_pk_fma_f32 v[38:39], v[36:37], v[136:137], v[38:39] op_sel_hi:[1,0,1]
	v_pk_fma_f32 v[6:7], v[4:5], v[140:141], v[6:7] op_sel_hi:[1,0,1]
	v_pk_fma_f32 v[56:57], v[54:55], v[76:77], v[56:57] op_sel_hi:[1,0,1]
	v_pk_fma_f32 v[24:25], v[22:23], v[130:131], v[24:25] op_sel_hi:[1,0,1]
	v_pk_fma_f32 v[40:41], v[54:55], v[76:77], v[40:41] op_sel:[0,1,0] op_sel_hi:[1,1,1]
	v_pk_fma_f32 v[8:9], v[22:23], v[130:131], v[8:9] op_sel:[0,1,0] op_sel_hi:[1,1,1]
	v_pk_fma_f32 v[56:57], v[38:39], v[76:77], v[56:57] op_sel:[0,1,0] op_sel_hi:[1,1,1] neg_lo:[0,1,0] neg_hi:[0,1,0]
	v_pk_fma_f32 v[24:25], v[6:7], v[130:131], v[24:25] op_sel:[0,1,0] op_sel_hi:[1,1,1] neg_lo:[0,1,0] neg_hi:[0,1,0]
	v_pk_fma_f32 v[40:41], v[38:39], v[76:77], v[40:41] op_sel_hi:[1,0,1]
	v_pk_fma_f32 v[8:9], v[6:7], v[130:131], v[8:9] op_sel_hi:[1,0,1]
	v_pk_fma_f32 v[58:59], v[56:57], v[136:137], v[58:59] op_sel_hi:[1,0,1]
	v_pk_fma_f32 v[26:27], v[24:25], v[140:141], v[26:27] op_sel_hi:[1,0,1]
	v_pk_fma_f32 v[42:43], v[56:57], v[136:137], v[42:43] op_sel:[0,1,0] op_sel_hi:[1,1,1]
	v_pk_fma_f32 v[10:11], v[24:25], v[140:141], v[10:11] op_sel:[0,1,0] op_sel_hi:[1,1,1]
	v_pk_fma_f32 v[58:59], v[40:41], v[136:137], v[58:59] op_sel:[0,1,0] op_sel_hi:[1,1,1] neg_lo:[0,1,0] neg_hi:[0,1,0]
	v_pk_fma_f32 v[26:27], v[8:9], v[140:141], v[26:27] op_sel:[0,1,0] op_sel_hi:[1,1,1] neg_lo:[0,1,0] neg_hi:[0,1,0]
	v_pk_fma_f32 v[42:43], v[40:41], v[136:137], v[42:43] op_sel_hi:[1,0,1]
	v_pk_fma_f32 v[10:11], v[8:9], v[140:141], v[10:11] op_sel_hi:[1,0,1]
	v_pk_fma_f32 v[60:61], v[58:59], v[76:77], v[60:61] op_sel_hi:[1,0,1]
	v_pk_fma_f32 v[28:29], v[26:27], v[130:131], v[28:29] op_sel_hi:[1,0,1]
	v_pk_fma_f32 v[44:45], v[58:59], v[76:77], v[44:45] op_sel:[0,1,0] op_sel_hi:[1,1,1]
	v_pk_fma_f32 v[12:13], v[26:27], v[130:131], v[12:13] op_sel:[0,1,0] op_sel_hi:[1,1,1]
	v_pk_fma_f32 v[60:61], v[42:43], v[76:77], v[60:61] op_sel:[0,1,0] op_sel_hi:[1,1,1] neg_lo:[0,1,0] neg_hi:[0,1,0]
	v_pk_fma_f32 v[28:29], v[10:11], v[130:131], v[28:29] op_sel:[0,1,0] op_sel_hi:[1,1,1] neg_lo:[0,1,0] neg_hi:[0,1,0]
	v_pk_fma_f32 v[44:45], v[42:43], v[76:77], v[44:45] op_sel_hi:[1,0,1]
	v_pk_fma_f32 v[12:13], v[10:11], v[130:131], v[12:13] op_sel_hi:[1,0,1]
	v_pk_fma_f32 v[62:63], v[60:61], v[136:137], v[62:63] op_sel_hi:[1,0,1]
	v_pk_fma_f32 v[30:31], v[28:29], v[140:141], v[30:31] op_sel_hi:[1,0,1]
	v_pk_fma_f32 v[46:47], v[60:61], v[136:137], v[46:47] op_sel:[0,1,0] op_sel_hi:[1,1,1]
	v_pk_fma_f32 v[14:15], v[28:29], v[140:141], v[14:15] op_sel:[0,1,0] op_sel_hi:[1,1,1]
	v_pk_fma_f32 v[62:63], v[44:45], v[136:137], v[62:63] op_sel:[0,1,0] op_sel_hi:[1,1,1] neg_lo:[0,1,0] neg_hi:[0,1,0]
	v_pk_fma_f32 v[30:31], v[12:13], v[140:141], v[30:31] op_sel:[0,1,0] op_sel_hi:[1,1,1] neg_lo:[0,1,0] neg_hi:[0,1,0]
	v_pk_fma_f32 v[46:47], v[44:45], v[136:137], v[46:47] op_sel_hi:[1,0,1]
	v_pk_fma_f32 v[14:15], v[12:13], v[140:141], v[14:15] op_sel_hi:[1,0,1]
	v_pk_fma_f32 v[64:65], v[62:63], v[76:77], v[64:65] op_sel_hi:[1,0,1]
	v_pk_fma_f32 v[32:33], v[30:31], v[130:131], v[32:33] op_sel_hi:[1,0,1]
	v_pk_fma_f32 v[48:49], v[62:63], v[76:77], v[48:49] op_sel:[0,1,0] op_sel_hi:[1,1,1]
	v_pk_fma_f32 v[16:17], v[30:31], v[130:131], v[16:17] op_sel:[0,1,0] op_sel_hi:[1,1,1]
	v_pk_fma_f32 v[64:65], v[46:47], v[76:77], v[64:65] op_sel:[0,1,0] op_sel_hi:[1,1,1] neg_lo:[0,1,0] neg_hi:[0,1,0]
	v_pk_fma_f32 v[32:33], v[14:15], v[130:131], v[32:33] op_sel:[0,1,0] op_sel_hi:[1,1,1] neg_lo:[0,1,0] neg_hi:[0,1,0]
	v_pk_fma_f32 v[48:49], v[46:47], v[76:77], v[48:49] op_sel_hi:[1,0,1]
	v_pk_fma_f32 v[16:17], v[14:15], v[130:131], v[16:17] op_sel_hi:[1,0,1]
	v_fmac_f32_e32 v65, v74, v64
	v_fmac_f32_e32 v33, v128, v32
	v_fmac_f32_e32 v49, v75, v64
	v_fmac_f32_e32 v17, v129, v32
	v_fma_f32 v65, -v75, v48, v65
	v_fma_f32 v33, -v129, v16, v33
	v_fmac_f32_e32 v49, v74, v48
	v_fmac_f32_e32 v17, v128, v16
	v_mov_b32_e32 v148, v144
	v_mov_b32_e32 v149, v146
	v_fma_f32 v144, v138, v144, v65
	v_fma_f32 v146, v142, v146, v33
	v_fma_f32 v144, -v139, v145, v144
	v_fma_f32 v146, -v143, v147, v146
	v_fma_f32 v145, v138, v145, v49
	v_fma_f32 v147, v142, v147, v17
	v_fmac_f32_e32 v145, v139, v148
	v_fmac_f32_e32 v147, v143, v149
	s_waitcnt vmcnt(1)
	v_mfma_f32_32x32x16_bf16 v[50:65], v[98:101], v[90:93], 0
	v_mfma_f32_32x32x16_bf16 v[18:33], v[98:101], v[86:89], 0
	v_mfma_f32_32x32x16_bf16 v[34:49], v[98:101], v[78:81], 0
	v_mfma_f32_32x32x16_bf16 v[2:17], v[98:101], v[82:85], 0
	s_nop 11
	v_pk_fma_f32 v[52:53], v[50:51], v[76:77], v[52:53] op_sel_hi:[1,0,1]
	v_pk_fma_f32 v[20:21], v[18:19], v[130:131], v[20:21] op_sel_hi:[1,0,1]
	v_pk_fma_f32 v[36:37], v[50:51], v[76:77], v[36:37] op_sel:[0,1,0] op_sel_hi:[1,1,1]
	v_pk_fma_f32 v[4:5], v[18:19], v[130:131], v[4:5] op_sel:[0,1,0] op_sel_hi:[1,1,1]
	v_pk_fma_f32 v[52:53], v[34:35], v[76:77], v[52:53] op_sel:[0,1,0] op_sel_hi:[1,1,1] neg_lo:[0,1,0] neg_hi:[0,1,0]
	v_pk_fma_f32 v[20:21], v[2:3], v[130:131], v[20:21] op_sel:[0,1,0] op_sel_hi:[1,1,1] neg_lo:[0,1,0] neg_hi:[0,1,0]
	v_pk_fma_f32 v[36:37], v[34:35], v[76:77], v[36:37] op_sel_hi:[1,0,1]
	v_pk_fma_f32 v[4:5], v[2:3], v[130:131], v[4:5] op_sel_hi:[1,0,1]
	v_pk_fma_f32 v[54:55], v[52:53], v[136:137], v[54:55] op_sel_hi:[1,0,1]
	v_pk_fma_f32 v[22:23], v[20:21], v[140:141], v[22:23] op_sel_hi:[1,0,1]
	v_pk_fma_f32 v[38:39], v[52:53], v[136:137], v[38:39] op_sel:[0,1,0] op_sel_hi:[1,1,1]
	v_pk_fma_f32 v[6:7], v[20:21], v[140:141], v[6:7] op_sel:[0,1,0] op_sel_hi:[1,1,1]
	v_pk_fma_f32 v[54:55], v[36:37], v[136:137], v[54:55] op_sel:[0,1,0] op_sel_hi:[1,1,1] neg_lo:[0,1,0] neg_hi:[0,1,0]
	v_pk_fma_f32 v[22:23], v[4:5], v[140:141], v[22:23] op_sel:[0,1,0] op_sel_hi:[1,1,1] neg_lo:[0,1,0] neg_hi:[0,1,0]
	v_pk_fma_f32 v[38:39], v[36:37], v[136:137], v[38:39] op_sel_hi:[1,0,1]
	v_pk_fma_f32 v[6:7], v[4:5], v[140:141], v[6:7] op_sel_hi:[1,0,1]
	v_pk_fma_f32 v[56:57], v[54:55], v[76:77], v[56:57] op_sel_hi:[1,0,1]
	v_pk_fma_f32 v[24:25], v[22:23], v[130:131], v[24:25] op_sel_hi:[1,0,1]
	v_pk_fma_f32 v[40:41], v[54:55], v[76:77], v[40:41] op_sel:[0,1,0] op_sel_hi:[1,1,1]
	v_pk_fma_f32 v[8:9], v[22:23], v[130:131], v[8:9] op_sel:[0,1,0] op_sel_hi:[1,1,1]
	v_pk_fma_f32 v[56:57], v[38:39], v[76:77], v[56:57] op_sel:[0,1,0] op_sel_hi:[1,1,1] neg_lo:[0,1,0] neg_hi:[0,1,0]
	v_pk_fma_f32 v[24:25], v[6:7], v[130:131], v[24:25] op_sel:[0,1,0] op_sel_hi:[1,1,1] neg_lo:[0,1,0] neg_hi:[0,1,0]
	v_pk_fma_f32 v[40:41], v[38:39], v[76:77], v[40:41] op_sel_hi:[1,0,1]
	v_pk_fma_f32 v[8:9], v[6:7], v[130:131], v[8:9] op_sel_hi:[1,0,1]
	v_pk_fma_f32 v[58:59], v[56:57], v[136:137], v[58:59] op_sel_hi:[1,0,1]
	v_pk_fma_f32 v[26:27], v[24:25], v[140:141], v[26:27] op_sel_hi:[1,0,1]
	v_pk_fma_f32 v[42:43], v[56:57], v[136:137], v[42:43] op_sel:[0,1,0] op_sel_hi:[1,1,1]
	v_pk_fma_f32 v[10:11], v[24:25], v[140:141], v[10:11] op_sel:[0,1,0] op_sel_hi:[1,1,1]
	v_pk_fma_f32 v[58:59], v[40:41], v[136:137], v[58:59] op_sel:[0,1,0] op_sel_hi:[1,1,1] neg_lo:[0,1,0] neg_hi:[0,1,0]
	v_pk_fma_f32 v[26:27], v[8:9], v[140:141], v[26:27] op_sel:[0,1,0] op_sel_hi:[1,1,1] neg_lo:[0,1,0] neg_hi:[0,1,0]
	v_pk_fma_f32 v[42:43], v[40:41], v[136:137], v[42:43] op_sel_hi:[1,0,1]
	v_pk_fma_f32 v[10:11], v[8:9], v[140:141], v[10:11] op_sel_hi:[1,0,1]
	v_pk_fma_f32 v[60:61], v[58:59], v[76:77], v[60:61] op_sel_hi:[1,0,1]
	v_pk_fma_f32 v[28:29], v[26:27], v[130:131], v[28:29] op_sel_hi:[1,0,1]
	v_pk_fma_f32 v[44:45], v[58:59], v[76:77], v[44:45] op_sel:[0,1,0] op_sel_hi:[1,1,1]
	v_pk_fma_f32 v[12:13], v[26:27], v[130:131], v[12:13] op_sel:[0,1,0] op_sel_hi:[1,1,1]
	v_pk_fma_f32 v[60:61], v[42:43], v[76:77], v[60:61] op_sel:[0,1,0] op_sel_hi:[1,1,1] neg_lo:[0,1,0] neg_hi:[0,1,0]
	v_pk_fma_f32 v[28:29], v[10:11], v[130:131], v[28:29] op_sel:[0,1,0] op_sel_hi:[1,1,1] neg_lo:[0,1,0] neg_hi:[0,1,0]
	v_pk_fma_f32 v[44:45], v[42:43], v[76:77], v[44:45] op_sel_hi:[1,0,1]
	v_pk_fma_f32 v[12:13], v[10:11], v[130:131], v[12:13] op_sel_hi:[1,0,1]
	v_pk_fma_f32 v[62:63], v[60:61], v[136:137], v[62:63] op_sel_hi:[1,0,1]
	v_pk_fma_f32 v[30:31], v[28:29], v[140:141], v[30:31] op_sel_hi:[1,0,1]
	v_pk_fma_f32 v[46:47], v[60:61], v[136:137], v[46:47] op_sel:[0,1,0] op_sel_hi:[1,1,1]
	v_pk_fma_f32 v[14:15], v[28:29], v[140:141], v[14:15] op_sel:[0,1,0] op_sel_hi:[1,1,1]
	v_pk_fma_f32 v[62:63], v[44:45], v[136:137], v[62:63] op_sel:[0,1,0] op_sel_hi:[1,1,1] neg_lo:[0,1,0] neg_hi:[0,1,0]
	v_pk_fma_f32 v[30:31], v[12:13], v[140:141], v[30:31] op_sel:[0,1,0] op_sel_hi:[1,1,1] neg_lo:[0,1,0] neg_hi:[0,1,0]
	v_pk_fma_f32 v[46:47], v[44:45], v[136:137], v[46:47] op_sel_hi:[1,0,1]
	v_pk_fma_f32 v[14:15], v[12:13], v[140:141], v[14:15] op_sel_hi:[1,0,1]
	v_pk_fma_f32 v[64:65], v[62:63], v[76:77], v[64:65] op_sel_hi:[1,0,1]
	v_pk_fma_f32 v[32:33], v[30:31], v[130:131], v[32:33] op_sel_hi:[1,0,1]
	v_pk_fma_f32 v[48:49], v[62:63], v[76:77], v[48:49] op_sel:[0,1,0] op_sel_hi:[1,1,1]
	v_pk_fma_f32 v[16:17], v[30:31], v[130:131], v[16:17] op_sel:[0,1,0] op_sel_hi:[1,1,1]
	v_pk_fma_f32 v[64:65], v[46:47], v[76:77], v[64:65] op_sel:[0,1,0] op_sel_hi:[1,1,1] neg_lo:[0,1,0] neg_hi:[0,1,0]
	v_pk_fma_f32 v[32:33], v[14:15], v[130:131], v[32:33] op_sel:[0,1,0] op_sel_hi:[1,1,1] neg_lo:[0,1,0] neg_hi:[0,1,0]
	v_pk_fma_f32 v[48:49], v[46:47], v[76:77], v[48:49] op_sel_hi:[1,0,1]
	v_pk_fma_f32 v[16:17], v[14:15], v[130:131], v[16:17] op_sel_hi:[1,0,1]
	v_fmac_f32_e32 v65, v74, v64
	v_fmac_f32_e32 v33, v128, v32
	v_fmac_f32_e32 v49, v75, v64
	v_fmac_f32_e32 v17, v129, v32
	v_fma_f32 v65, -v75, v48, v65
	v_fma_f32 v33, -v129, v16, v33
	v_fmac_f32_e32 v49, v74, v48
	v_fmac_f32_e32 v17, v128, v16
	v_mov_b32_e32 v148, v144
	v_mov_b32_e32 v149, v146
	v_fma_f32 v144, v138, v144, v65
	v_fma_f32 v146, v142, v146, v33
	v_fma_f32 v144, -v139, v145, v144
	v_fma_f32 v146, -v143, v147, v146
	v_fma_f32 v145, v138, v145, v49
	v_fma_f32 v147, v142, v147, v17
	v_fmac_f32_e32 v145, v139, v148
	v_fmac_f32_e32 v147, v143, v149
	s_waitcnt vmcnt(0)
	v_mfma_f32_32x32x16_bf16 v[50:65], v[94:97], v[90:93], 0
	v_mfma_f32_32x32x16_bf16 v[18:33], v[94:97], v[86:89], 0
	v_mfma_f32_32x32x16_bf16 v[34:49], v[94:97], v[78:81], 0
	v_mfma_f32_32x32x16_bf16 v[2:17], v[94:97], v[82:85], 0
	s_nop 11
	v_pk_fma_f32 v[52:53], v[50:51], v[76:77], v[52:53] op_sel_hi:[1,0,1]
	v_pk_fma_f32 v[20:21], v[18:19], v[130:131], v[20:21] op_sel_hi:[1,0,1]
	v_pk_fma_f32 v[36:37], v[50:51], v[76:77], v[36:37] op_sel:[0,1,0] op_sel_hi:[1,1,1]
	v_pk_fma_f32 v[4:5], v[18:19], v[130:131], v[4:5] op_sel:[0,1,0] op_sel_hi:[1,1,1]
	v_pk_fma_f32 v[52:53], v[34:35], v[76:77], v[52:53] op_sel:[0,1,0] op_sel_hi:[1,1,1] neg_lo:[0,1,0] neg_hi:[0,1,0]
	v_pk_fma_f32 v[20:21], v[2:3], v[130:131], v[20:21] op_sel:[0,1,0] op_sel_hi:[1,1,1] neg_lo:[0,1,0] neg_hi:[0,1,0]
	v_pk_fma_f32 v[36:37], v[34:35], v[76:77], v[36:37] op_sel_hi:[1,0,1]
	v_pk_fma_f32 v[4:5], v[2:3], v[130:131], v[4:5] op_sel_hi:[1,0,1]
	v_pk_fma_f32 v[54:55], v[52:53], v[136:137], v[54:55] op_sel_hi:[1,0,1]
	v_pk_fma_f32 v[22:23], v[20:21], v[140:141], v[22:23] op_sel_hi:[1,0,1]
	v_pk_fma_f32 v[38:39], v[52:53], v[136:137], v[38:39] op_sel:[0,1,0] op_sel_hi:[1,1,1]
	v_pk_fma_f32 v[6:7], v[20:21], v[140:141], v[6:7] op_sel:[0,1,0] op_sel_hi:[1,1,1]
	v_pk_fma_f32 v[54:55], v[36:37], v[136:137], v[54:55] op_sel:[0,1,0] op_sel_hi:[1,1,1] neg_lo:[0,1,0] neg_hi:[0,1,0]
	v_pk_fma_f32 v[22:23], v[4:5], v[140:141], v[22:23] op_sel:[0,1,0] op_sel_hi:[1,1,1] neg_lo:[0,1,0] neg_hi:[0,1,0]
	v_pk_fma_f32 v[38:39], v[36:37], v[136:137], v[38:39] op_sel_hi:[1,0,1]
	v_pk_fma_f32 v[6:7], v[4:5], v[140:141], v[6:7] op_sel_hi:[1,0,1]
	v_pk_fma_f32 v[56:57], v[54:55], v[76:77], v[56:57] op_sel_hi:[1,0,1]
	v_pk_fma_f32 v[24:25], v[22:23], v[130:131], v[24:25] op_sel_hi:[1,0,1]
	v_pk_fma_f32 v[40:41], v[54:55], v[76:77], v[40:41] op_sel:[0,1,0] op_sel_hi:[1,1,1]
	v_pk_fma_f32 v[8:9], v[22:23], v[130:131], v[8:9] op_sel:[0,1,0] op_sel_hi:[1,1,1]
	v_pk_fma_f32 v[56:57], v[38:39], v[76:77], v[56:57] op_sel:[0,1,0] op_sel_hi:[1,1,1] neg_lo:[0,1,0] neg_hi:[0,1,0]
	v_pk_fma_f32 v[24:25], v[6:7], v[130:131], v[24:25] op_sel:[0,1,0] op_sel_hi:[1,1,1] neg_lo:[0,1,0] neg_hi:[0,1,0]
	v_pk_fma_f32 v[40:41], v[38:39], v[76:77], v[40:41] op_sel_hi:[1,0,1]
	v_pk_fma_f32 v[8:9], v[6:7], v[130:131], v[8:9] op_sel_hi:[1,0,1]
	v_pk_fma_f32 v[58:59], v[56:57], v[136:137], v[58:59] op_sel_hi:[1,0,1]
	v_pk_fma_f32 v[26:27], v[24:25], v[140:141], v[26:27] op_sel_hi:[1,0,1]
	v_pk_fma_f32 v[42:43], v[56:57], v[136:137], v[42:43] op_sel:[0,1,0] op_sel_hi:[1,1,1]
	v_pk_fma_f32 v[10:11], v[24:25], v[140:141], v[10:11] op_sel:[0,1,0] op_sel_hi:[1,1,1]
	v_pk_fma_f32 v[58:59], v[40:41], v[136:137], v[58:59] op_sel:[0,1,0] op_sel_hi:[1,1,1] neg_lo:[0,1,0] neg_hi:[0,1,0]
	v_pk_fma_f32 v[26:27], v[8:9], v[140:141], v[26:27] op_sel:[0,1,0] op_sel_hi:[1,1,1] neg_lo:[0,1,0] neg_hi:[0,1,0]
	v_pk_fma_f32 v[42:43], v[40:41], v[136:137], v[42:43] op_sel_hi:[1,0,1]
	v_pk_fma_f32 v[10:11], v[8:9], v[140:141], v[10:11] op_sel_hi:[1,0,1]
	v_pk_fma_f32 v[60:61], v[58:59], v[76:77], v[60:61] op_sel_hi:[1,0,1]
	v_pk_fma_f32 v[28:29], v[26:27], v[130:131], v[28:29] op_sel_hi:[1,0,1]
	v_pk_fma_f32 v[44:45], v[58:59], v[76:77], v[44:45] op_sel:[0,1,0] op_sel_hi:[1,1,1]
	v_pk_fma_f32 v[12:13], v[26:27], v[130:131], v[12:13] op_sel:[0,1,0] op_sel_hi:[1,1,1]
	v_pk_fma_f32 v[60:61], v[42:43], v[76:77], v[60:61] op_sel:[0,1,0] op_sel_hi:[1,1,1] neg_lo:[0,1,0] neg_hi:[0,1,0]
	v_pk_fma_f32 v[28:29], v[10:11], v[130:131], v[28:29] op_sel:[0,1,0] op_sel_hi:[1,1,1] neg_lo:[0,1,0] neg_hi:[0,1,0]
	v_pk_fma_f32 v[44:45], v[42:43], v[76:77], v[44:45] op_sel_hi:[1,0,1]
	v_pk_fma_f32 v[12:13], v[10:11], v[130:131], v[12:13] op_sel_hi:[1,0,1]
	v_pk_fma_f32 v[62:63], v[60:61], v[136:137], v[62:63] op_sel_hi:[1,0,1]
	v_pk_fma_f32 v[30:31], v[28:29], v[140:141], v[30:31] op_sel_hi:[1,0,1]
	v_pk_fma_f32 v[46:47], v[60:61], v[136:137], v[46:47] op_sel:[0,1,0] op_sel_hi:[1,1,1]
	v_pk_fma_f32 v[14:15], v[28:29], v[140:141], v[14:15] op_sel:[0,1,0] op_sel_hi:[1,1,1]
	v_pk_fma_f32 v[62:63], v[44:45], v[136:137], v[62:63] op_sel:[0,1,0] op_sel_hi:[1,1,1] neg_lo:[0,1,0] neg_hi:[0,1,0]
	v_pk_fma_f32 v[30:31], v[12:13], v[140:141], v[30:31] op_sel:[0,1,0] op_sel_hi:[1,1,1] neg_lo:[0,1,0] neg_hi:[0,1,0]
	v_pk_fma_f32 v[46:47], v[44:45], v[136:137], v[46:47] op_sel_hi:[1,0,1]
	v_pk_fma_f32 v[14:15], v[12:13], v[140:141], v[14:15] op_sel_hi:[1,0,1]
	v_pk_fma_f32 v[64:65], v[62:63], v[76:77], v[64:65] op_sel_hi:[1,0,1]
	v_pk_fma_f32 v[32:33], v[30:31], v[130:131], v[32:33] op_sel_hi:[1,0,1]
	v_pk_fma_f32 v[48:49], v[62:63], v[76:77], v[48:49] op_sel:[0,1,0] op_sel_hi:[1,1,1]
	v_pk_fma_f32 v[16:17], v[30:31], v[130:131], v[16:17] op_sel:[0,1,0] op_sel_hi:[1,1,1]
	v_pk_fma_f32 v[64:65], v[46:47], v[76:77], v[64:65] op_sel:[0,1,0] op_sel_hi:[1,1,1] neg_lo:[0,1,0] neg_hi:[0,1,0]
	v_pk_fma_f32 v[32:33], v[14:15], v[130:131], v[32:33] op_sel:[0,1,0] op_sel_hi:[1,1,1] neg_lo:[0,1,0] neg_hi:[0,1,0]
	v_pk_fma_f32 v[48:49], v[46:47], v[76:77], v[48:49] op_sel_hi:[1,0,1]
	v_pk_fma_f32 v[16:17], v[14:15], v[130:131], v[16:17] op_sel_hi:[1,0,1]
	v_fmac_f32_e32 v65, v74, v64
	v_fmac_f32_e32 v33, v128, v32
	v_fmac_f32_e32 v49, v75, v64
	v_fmac_f32_e32 v17, v129, v32
	v_fma_f32 v65, -v75, v48, v65
	v_fma_f32 v33, -v129, v16, v33
	v_fmac_f32_e32 v49, v74, v48
	v_fmac_f32_e32 v17, v128, v16
	v_mov_b32_e32 v148, v144
	v_mov_b32_e32 v149, v146
	v_fma_f32 v144, v138, v144, v65
	v_fma_f32 v146, v142, v146, v33
	v_fma_f32 v144, -v139, v145, v144
	v_fma_f32 v146, -v143, v147, v146
	v_fma_f32 v145, v138, v145, v49
	v_fma_f32 v147, v142, v147, v17
	v_fmac_f32_e32 v145, v139, v148
	v_fmac_f32_e32 v147, v143, v149
	v_mov_b32_e32 v148, v144
	v_mov_b32_e32 v149, v146
	v_mov_b32_e32 v150, v145
	v_mov_b32_e32 v151, v147
	s_nop 1
	v_permlane32_swap_b32_e32 v148, v144
	v_permlane32_swap_b32_e32 v149, v146
	v_permlane32_swap_b32_e32 v150, v145
	v_permlane32_swap_b32_e32 v151, v147
	v_fma_f32 v34, v72, v148, v144
	v_fma_f32 v35, v72, v150, v145
	v_fma_f32 v2, v134, v149, v146
	v_fma_f32 v3, v134, v151, v147
	v_fma_f32 v34, -v73, v150, v34
	v_fmac_f32_e32 v35, v73, v148
	v_fma_f32 v2, -v135, v151, v2
	v_fmac_f32_e32 v3, v135, v149
	s_and_saveexec_b64 s[4:5], vcc
	s_cbranch_execz .LBB0_749
	s_and_b32 s2, s16, 0xfffffc00
	s_lshl_b32 s11, s11, 5
	s_or_b32 s2, s11, s2
	s_or_b32 s10, s2, s10
	s_ashr_i32 s11, s10, 31
	s_lshl_b64 s[10:11], s[10:11], 9
	s_add_u32 s10, s14, s10
	s_addc_u32 s11, s15, s11
	v_lshlrev_b32_e32 v4, 3, v123
	global_store_dwordx2 v4, v[34:35], s[10:11] sc1
	global_store_dwordx2 v4, v[2:3], s[10:11] offset:256 sc1
